# stack v68 + gmlp: the four norm-weight loads issued together at the first use site with counted waits (one round trip instead of four)
# baseline (speedup 1.0000x reference)
; #define LAS __attribute__((address_space(3)))
; __device__ __forceinline__ float bflo(unsigned w) { return __uint_as_float(w << 16); }
; __device__ __forceinline__ float bfhi(unsigned w) { return __uint_as_float(w & 0xffff0000u); }
; __device__ __forceinline__ float gelu_t(float x) { return x * sigm(1.5957691216057308f * (x + 0.044715f * x * x * x)); }
; __device__ __forceinline__ void lds_barrier() { asm volatile("s_waitcnt lgkmcnt(0)" ::: "memory"); __builtin_amdgcn_s_barrier(); asm volatile("" ::: "memory"); }
; __device__ __forceinline__ int opaque_tid() { int t = threadIdx.x; asm volatile("" : "+v"(t)); return t; }
; __device__ __forceinline__ void gmlp_item(const Params& p, int l, int item, LAS unsigned char* lds) {
;     const int tid = opaque_tid(), wid = tid >> 6, lane = tid & 63, fr = lane & 15, fq = lane >> 4;
;     const int b = item >> 6, blk = (item >> 2) & 15, g = item & 3;
;     LAS bf16_t* vnT = (LAS bf16_t*)lds;
;     const size_t T0 = (size_t)b * SEQ + blk * 128;
;     lds_barrier();
;     const int nks = (wid >> 1) + 1;
;     const size_t Tw = T0 + wid * 16 + fr;
;     bf16x8 bwp[4]; u32x2 uwp[4];
;     { const bf16_t* wp = p.gmw + (((size_t)l * 4 + g) * 128 + wid * 16 + fr) * 128 + fq * 8;
; #pragma unroll
;       for (int ks = 0; ks < 4; ++ks) bwp[ks] = *(const bf16x8*)(wp + (ks < nks ? ks : 0) * 32);
; #pragma unroll
;       for (int ct = 0; ct < 4; ++ct) uwp[ct] = *(const u32x2*)(p.z + Tw * ZLD + 1792 + g * 64 + ct * 16 + fq * 4); }
;     const float bsv = p.gm_bs[((size_t)l * 4 + g) * 128 + wid * 16 + fr];
;     { const int pp = tid >> 2, qd = tid & 3; const bf16_t* vp = p.z + (T0 + pp) * ZLD + 2048 + qd * 16;
;       float keep[16]; float ss = 0.f;
; #pragma unroll
;       for (int i = 0; i < 16; ++i) keep[i] = 0.f;
; #pragma unroll
;       for (int gg = 0; gg < 4; ++gg) { const u32x4 w0 = *(const u32x4*)(vp + gg * 64), w1 = *(const u32x4*)(vp + gg * 64 + 8);
;           const float v[16] = {bflo(w0.x), bfhi(w0.x), bflo(w0.y), bfhi(w0.y), bflo(w0.z), bfhi(w0.z), bflo(w0.w), bfhi(w0.w),
;                                bflo(w1.x), bfhi(w1.x), bflo(w1.y), bfhi(w1.y), bflo(w1.z), bfhi(w1.z), bflo(w1.w), bfhi(w1.w)};
; #pragma unroll
;           for (int i = 0; i < 16; ++i) { const float ge = gelu_t(v[i]); ss += ge * ge; keep[i] = (gg == g) ? ge : keep[i]; } }
.LBB0_319:
	s_and_b64 vcc, exec, s[6:7]
	s_cbranch_vccz .LBB0_342
	v_mov_b32_e32 v34, v202
	s_bfe_u32 s37, s72, 0x20003
	s_lshl_b32 s96, s37, 7
	v_ashrrev_i32_e32 v30, 2, v34
	v_and_b32_e32 v32, 15, v34
	v_and_b32_e32 v0, -16, v30
	s_or_b32 s6, s26, s96
	v_ashrrev_i32_e32 v1, 31, v0
	v_or_b32_e32 v4, s6, v32
	v_mov_b32_e32 v5, s27
	v_lshl_add_u64 v[22:23], v[4:5], 0, v[0:1]
	v_bfe_u32 v48, v34, 4, 2
	v_ashrrev_i32_e32 v33, 7, v34
	v_lshlrev_b64 v[4:5], 8, v[22:23]
	v_lshl_add_u64 v[4:5], s[4:5], 0, v[4:5]
	v_lshlrev_b32_e32 v28, 4, v48
	v_mov_b32_e32 v29, v2
	v_cmp_gt_i32_e32 vcc, 1, v33
	v_lshl_add_u64 v[4:5], v[4:5], 0, v[28:29]
	v_mov_b32_e32 v7, v2
	v_cndmask_b32_e64 v6, 64, 0, vcc
	v_mov_b32_e32 v20, s0
	s_add_i32 s0, s21, 0xffffff00
	s_waitcnt lgkmcnt(0)
	s_barrier
	v_lshl_add_u64 v[6:7], v[4:5], 0, v[6:7]
	v_cmp_gt_i32_e32 vcc, 2, v33
	v_mov_b32_e32 v21, s14
	s_ashr_i32 s14, s0, 6
	global_load_dwordx4 v[16:19], v[4:5], off
	global_load_dwordx4 v[12:15], v[6:7], off
	v_cndmask_b32_e64 v6, v243, 0, vcc
	v_mov_b32_e32 v7, v2
	s_ashr_i32 s15, s14, 31
	s_lshl_b32 s0, s16, 5
	v_lshl_add_u64 v[6:7], v[4:5], 0, v[6:7]
	v_cmp_gt_i32_e64 s[8:9], 3, v33
	s_and_b32 s0, s0, 0x780
	global_load_dwordx4 v[8:11], v[6:7], off
	v_cndmask_b32_e64 v6, v254, 0, s[8:9]
	s_lshl_b64 s[8:9], s[14:15], 11
	s_or_b32 s8, s8, s0
	v_lshl_add_u64 v[46:47], s[8:9], 0, v[0:1]
	v_or_b32_e32 v46, v46, v32
	v_mov_b64_e32 v[26:27], s[34:35]
	s_movk_i32 s0, 0x1600
	v_mad_u64_u32 v[0:1], s[14:15], v46, s0, v[26:27]
	v_mad_i32_i24 v1, v47, s0, v1
	v_lshlrev_b32_e32 v24, 3, v48
	v_mov_b32_e32 v25, v2
	v_mov_b32_e32 v7, v2
	v_lshl_add_u64 v[0:1], v[0:1], 0, s[96:97]
	v_lshl_add_u64 v[4:5], v[4:5], 0, v[6:7]
	v_lshl_add_u64 v[0:1], v[0:1], 0, v[24:25]
	v_lshl_add_u64 v[20:21], v[22:23], 2, v[20:21]
	v_ashrrev_i32_e32 v31, 31, v30
	global_load_dwordx4 v[4:7], v[4:5], off
	s_nop 0
	global_load_dwordx2 v[44:45], v[0:1], off offset:3584
	global_load_dwordx2 v[42:43], v[0:1], off offset:3616
	global_load_dwordx2 v[40:41], v[0:1], off offset:3648
	s_nop 0
	global_load_dwordx2 v[0:1], v[0:1], off offset:3680
	s_cmp_eq_u32 s37, 0
	global_load_dword v3, v[20:21], off
	v_lshl_add_u64 v[20:21], s[8:9], 0, v[30:31]
	v_mad_u64_u32 v[22:23], s[8:9], v20, s0, v[26:27]
	v_lshlrev_b32_e32 v20, 4, v34
	v_and_b32_e32 v29, 48, v20
	v_mad_i32_i24 v23, v21, s0, v23
	v_lshlrev_b32_e32 v20, 1, v29
	v_mov_b32_e32 v21, v2
	v_lshl_add_u64 v[20:21], v[22:23], 0, v[20:21]
	s_mov_b64 s[8:9], 0x1000
	v_lshl_add_u64 v[24:25], v[20:21], 0, s[8:9]
	v_add_co_u32_e64 v20, s[8:9], s80, v20
	v_lshlrev_b32_e32 v30, 1, v30
	s_nop 0
	v_addc_co_u32_e64 v21, s[8:9], 0, v21, s[8:9]
	global_load_dwordx4 v[20:23], v[20:21], off
	s_nop 0
	global_load_dwordx4 v[34:37], v[24:25], off offset:16
	global_load_dwordx4 v[102:105], v[24:25], off offset:144
	global_load_dwordx4 v[106:109], v[24:25], off offset:128
	global_load_dwordx4 v[110:113], v[24:25], off offset:272
	global_load_dwordx4 v[114:117], v[24:25], off offset:256
	global_load_dwordx4 v[118:121], v[24:25], off offset:400
	global_load_dwordx4 v[122:125], v[24:25], off offset:384
	s_cselect_b64 s[8:9], -1, 0
	s_cmp_eq_u32 s37, 1
	v_cmp_lt_i32_e64 s[6:7], 0, v33
	v_cmp_lt_i32_e64 s[4:5], 1, v33
	v_cmp_lt_i32_e32 vcc, 2, v33
	s_waitcnt vmcnt(7)
	v_lshlrev_b32_e32 v26, 16, v20
	v_mul_f32_e32 v31, 0x3d372713, v26
	v_mul_f32_e32 v31, v31, v26
	v_fma_f32 v31, v31, v26, v26
	v_mul_f32_e32 v31, 0x3fcc422a, v31
	v_mul_f32_e32 v31, 0xbfb8aa3b, v31
	v_exp_f32_e32 v31, v31
	v_and_b32_e32 v20, 0xffff0000, v20
	v_lshlrev_b32_e32 v27, 16, v21
	v_and_b32_e32 v21, 0xffff0000, v21
	v_add_f32_e32 v31, 1.0, v31
	v_rcp_f32_e32 v31, v31
	v_lshlrev_b32_e32 v38, 16, v22
	v_and_b32_e32 v22, 0xffff0000, v22
	v_lshlrev_b32_e32 v39, 16, v23
	v_mul_f32_e32 v26, v31, v26
	v_mul_f32_e32 v31, 0x3d372713, v20
	v_mul_f32_e32 v31, v31, v20
	v_fma_f32 v31, v31, v20, v20
	v_mul_f32_e32 v31, 0x3fcc422a, v31
	v_mul_f32_e32 v31, 0xbfb8aa3b, v31
	v_exp_f32_e32 v31, v31
	v_cndmask_b32_e64 v53, 0, v26, s[8:9]
	v_and_b32_e32 v23, 0xffff0000, v23
	s_waitcnt vmcnt(6)
	v_lshlrev_b32_e32 v49, 16, v34
	v_add_f32_e32 v31, 1.0, v31
	v_rcp_f32_e32 v31, v31
	v_and_b32_e32 v34, 0xffff0000, v34
	v_lshlrev_b32_e32 v50, 16, v35
	v_and_b32_e32 v35, 0xffff0000, v35
	v_mul_f32_e32 v20, v31, v20
	v_mul_f32_e32 v31, v20, v20
	v_fmac_f32_e32 v31, v26, v26
	v_cndmask_b32_e64 v26, 0, v20, s[8:9]
	v_mul_f32_e32 v20, 0x3d372713, v27
	v_mul_f32_e32 v20, v20, v27
	v_fma_f32 v20, v20, v27, v27
	v_mul_f32_e32 v20, 0x3fcc422a, v20
	v_mul_f32_e32 v20, 0xbfb8aa3b, v20
	v_exp_f32_e32 v20, v20
	v_lshlrev_b32_e32 v51, 16, v36
	v_and_b32_e32 v36, 0xffff0000, v36
	v_lshlrev_b32_e32 v52, 16, v37
	v_add_f32_e32 v20, 1.0, v20
	v_rcp_f32_e32 v20, v20
	v_and_b32_e32 v37, 0xffff0000, v37
	v_mul_f32_e32 v20, v20, v27
	v_fmac_f32_e32 v31, v20, v20
	v_cndmask_b32_e64 v27, 0, v20, s[8:9]
	v_mul_f32_e32 v20, 0x3d372713, v21
	v_mul_f32_e32 v20, v20, v21
	v_fma_f32 v20, v20, v21, v21
	v_mul_f32_e32 v20, 0x3fcc422a, v20
	v_mul_f32_e32 v20, 0xbfb8aa3b, v20
	v_exp_f32_e32 v20, v20
	s_nop 0
	v_add_f32_e32 v20, 1.0, v20
	v_rcp_f32_e32 v20, v20
	s_nop 0
	v_mul_f32_e32 v20, v20, v21
	v_fmac_f32_e32 v31, v20, v20
	v_cndmask_b32_e64 v54, 0, v20, s[8:9]
	v_mul_f32_e32 v20, 0x3d372713, v38
	v_mul_f32_e32 v20, v20, v38
	v_fma_f32 v20, v20, v38, v38
	v_mul_f32_e32 v20, 0x3fcc422a, v20
	v_mul_f32_e32 v20, 0xbfb8aa3b, v20
	v_exp_f32_e32 v20, v20
	s_nop 0
	v_add_f32_e32 v20, 1.0, v20
	v_rcp_f32_e32 v20, v20
	s_nop 0
	v_mul_f32_e32 v20, v20, v38
	v_fmac_f32_e32 v31, v20, v20
	v_cndmask_b32_e64 v38, 0, v20, s[8:9]
	v_mul_f32_e32 v20, 0x3d372713, v22
	v_mul_f32_e32 v20, v20, v22
; __device__ __forceinline__ float bflo(unsigned w) { return __uint_as_float(w << 16); }
; __device__ __forceinline__ float bfhi(unsigned w) { return __uint_as_float(w & 0xffff0000u); }
; __device__ __forceinline__ float gelu_t(float x) { return x * sigm(1.5957691216057308f * (x + 0.044715f * x * x * x)); }
; __device__ __forceinline__ void gmlp_item(const Params& p, int l, int item, LAS unsigned char* lds) {
;     ...
;       for (int gg = 0; gg < 4; ++gg) { const u32x4 w0 = *(const u32x4*)(vp + gg * 64), w1 = *(const u32x4*)(vp + gg * 64 + 8);
;           const float v[16] = {bflo(w0.x), bfhi(w0.x), bflo(w0.y), bfhi(w0.y), bflo(w0.z), bfhi(w0.z), bflo(w0.w), bfhi(w0.w),
;                                bflo(w1.x), bfhi(w1.x), bflo(w1.y), bfhi(w1.y), bflo(w1.z), bfhi(w1.z), bflo(w1.w), bfhi(w1.w)};
; #pragma unroll
;           for (int i = 0; i < 16; ++i) { const float ge = gelu_t(v[i]); ss += ge * ge; keep[i] = (gg == g) ? ge : keep[i]; } }
	v_fma_f32 v20, v20, v22, v22
	v_mul_f32_e32 v20, 0x3fcc422a, v20
	v_mul_f32_e32 v20, 0xbfb8aa3b, v20
	v_exp_f32_e32 v20, v20
	s_nop 0
	v_add_f32_e32 v20, 1.0, v20
	v_rcp_f32_e32 v20, v20
	s_nop 0
	v_mul_f32_e32 v20, v20, v22
	v_fmac_f32_e32 v31, v20, v20
	v_cndmask_b32_e64 v55, 0, v20, s[8:9]
	v_mul_f32_e32 v20, 0x3d372713, v39
	v_mul_f32_e32 v20, v20, v39
	v_fma_f32 v20, v20, v39, v39
	v_mul_f32_e32 v20, 0x3fcc422a, v20
	v_mul_f32_e32 v20, 0xbfb8aa3b, v20
	v_exp_f32_e32 v20, v20
	s_nop 0
	v_add_f32_e32 v20, 1.0, v20
	v_rcp_f32_e32 v20, v20
	s_nop 0
	v_mul_f32_e32 v20, v20, v39
	v_fmac_f32_e32 v31, v20, v20
	v_cndmask_b32_e64 v39, 0, v20, s[8:9]
	v_mul_f32_e32 v20, 0x3d372713, v23
	v_mul_f32_e32 v20, v20, v23
	v_fma_f32 v20, v20, v23, v23
	v_mul_f32_e32 v20, 0x3fcc422a, v20
	v_mul_f32_e32 v20, 0xbfb8aa3b, v20
	v_exp_f32_e32 v20, v20
	s_nop 0
	v_add_f32_e32 v20, 1.0, v20
	v_rcp_f32_e32 v20, v20
	s_nop 0
	v_mul_f32_e32 v20, v20, v23
	v_fmac_f32_e32 v31, v20, v20
	v_cndmask_b32_e64 v56, 0, v20, s[8:9]
	v_mul_f32_e32 v20, 0x3d372713, v49
	v_mul_f32_e32 v20, v20, v49
	v_fma_f32 v20, v20, v49, v49
	v_mul_f32_e32 v20, 0x3fcc422a, v20
	v_mul_f32_e32 v20, 0xbfb8aa3b, v20
	v_exp_f32_e32 v20, v20
	s_nop 0
	v_add_f32_e32 v20, 1.0, v20
	v_rcp_f32_e32 v20, v20
	s_nop 0
	v_mul_f32_e32 v20, v20, v49
	v_fmac_f32_e32 v31, v20, v20
	v_cndmask_b32_e64 v49, 0, v20, s[8:9]
	v_mul_f32_e32 v20, 0x3d372713, v34
	v_mul_f32_e32 v20, v20, v34
	v_fma_f32 v20, v20, v34, v34
	v_mul_f32_e32 v20, 0x3fcc422a, v20
	v_mul_f32_e32 v20, 0xbfb8aa3b, v20
	v_exp_f32_e32 v20, v20
	s_nop 0
	v_add_f32_e32 v20, 1.0, v20
	v_rcp_f32_e32 v20, v20
	s_nop 0
	v_mul_f32_e32 v20, v20, v34
	v_fmac_f32_e32 v31, v20, v20
	v_cndmask_b32_e64 v57, 0, v20, s[8:9]
	v_mul_f32_e32 v20, 0x3d372713, v50
	v_mul_f32_e32 v20, v20, v50
	v_fma_f32 v20, v20, v50, v50
	v_mul_f32_e32 v20, 0x3fcc422a, v20
	v_mul_f32_e32 v20, 0xbfb8aa3b, v20
	v_exp_f32_e32 v20, v20
	s_nop 0
	v_add_f32_e32 v20, 1.0, v20
	v_rcp_f32_e32 v20, v20
	s_nop 0
	v_mul_f32_e32 v20, v20, v50
	v_fmac_f32_e32 v31, v20, v20
	v_cndmask_b32_e64 v50, 0, v20, s[8:9]
	v_mul_f32_e32 v20, 0x3d372713, v35
	v_mul_f32_e32 v20, v20, v35
	v_fma_f32 v20, v20, v35, v35
	v_mul_f32_e32 v20, 0x3fcc422a, v20
	v_mul_f32_e32 v20, 0xbfb8aa3b, v20
	v_exp_f32_e32 v20, v20
	s_nop 0
	v_add_f32_e32 v20, 1.0, v20
	v_rcp_f32_e32 v20, v20
	s_nop 0
	v_mul_f32_e32 v20, v20, v35
	v_fmac_f32_e32 v31, v20, v20
	v_cndmask_b32_e64 v58, 0, v20, s[8:9]
	v_mul_f32_e32 v20, 0x3d372713, v51
	v_mul_f32_e32 v20, v20, v51
	v_fma_f32 v20, v20, v51, v51
	v_mul_f32_e32 v20, 0x3fcc422a, v20
	v_mul_f32_e32 v20, 0xbfb8aa3b, v20
	v_exp_f32_e32 v20, v20
	s_nop 0
	v_add_f32_e32 v20, 1.0, v20
	v_rcp_f32_e32 v20, v20
	s_nop 0
	v_mul_f32_e32 v20, v20, v51
	v_fmac_f32_e32 v31, v20, v20
	v_cndmask_b32_e64 v51, 0, v20, s[8:9]
	v_mul_f32_e32 v20, 0x3d372713, v36
	v_mul_f32_e32 v20, v20, v36
	v_fma_f32 v20, v20, v36, v36
	v_mul_f32_e32 v20, 0x3fcc422a, v20
	v_mul_f32_e32 v20, 0xbfb8aa3b, v20
	v_exp_f32_e32 v20, v20
	s_nop 0
	v_add_f32_e32 v20, 1.0, v20
	v_rcp_f32_e32 v20, v20
	s_nop 0
	v_mul_f32_e32 v20, v20, v36
	v_fmac_f32_e32 v31, v20, v20
	v_cndmask_b32_e64 v59, 0, v20, s[8:9]
	v_mul_f32_e32 v20, 0x3d372713, v52
	v_mul_f32_e32 v20, v20, v52
	v_fma_f32 v20, v20, v52, v52
	v_mul_f32_e32 v20, 0x3fcc422a, v20
	v_mul_f32_e32 v20, 0xbfb8aa3b, v20
	v_exp_f32_e32 v20, v20
	s_nop 0
	v_add_f32_e32 v20, 1.0, v20
	v_rcp_f32_e32 v20, v20
	s_nop 0
	v_mul_f32_e32 v20, v20, v52
	v_fmac_f32_e32 v31, v20, v20
	v_cndmask_b32_e64 v52, 0, v20, s[8:9]
	v_mul_f32_e32 v20, 0x3d372713, v37
	v_mul_f32_e32 v20, v20, v37
	v_fma_f32 v20, v20, v37, v37
	v_mul_f32_e32 v20, 0x3fcc422a, v20
	v_mul_f32_e32 v20, 0xbfb8aa3b, v20
	v_exp_f32_e32 v20, v20
	s_nop 0
	v_add_f32_e32 v20, 1.0, v20
	v_rcp_f32_e32 v20, v20
	s_nop 0
	v_mul_f32_e32 v20, v20, v37
	v_fmac_f32_e32 v31, v20, v20
	v_cndmask_b32_e64 v60, 0, v20, s[8:9]
	s_waitcnt vmcnt(4)
	v_mov_b32_e32 v20, v102
	v_mov_b32_e32 v21, v103
	v_mov_b32_e32 v22, v104
	v_mov_b32_e32 v23, v105
	v_mov_b32_e32 v34, v106
	v_mov_b32_e32 v35, v107
	v_mov_b32_e32 v36, v108
	v_mov_b32_e32 v37, v109
	s_cselect_b64 s[8:9], -1, 0
	s_cmp_eq_u32 s37, 2
	v_lshlrev_b32_e32 v65, 16, v20
	v_lshlrev_b32_e32 v61, 16, v34
	v_mul_f32_e32 v69, 0x3d372713, v61
	v_mul_f32_e32 v69, v69, v61
	v_fma_f32 v69, v69, v61, v61
	v_mul_f32_e32 v69, 0x3fcc422a, v69
	v_mul_f32_e32 v69, 0xbfb8aa3b, v69
	v_exp_f32_e32 v69, v69
	v_and_b32_e32 v34, 0xffff0000, v34
	v_lshlrev_b32_e32 v62, 16, v35
	v_and_b32_e32 v35, 0xffff0000, v35
	v_add_f32_e32 v69, 1.0, v69
	v_rcp_f32_e32 v69, v69
	v_lshlrev_b32_e32 v63, 16, v36
	v_and_b32_e32 v36, 0xffff0000, v36
	v_lshlrev_b32_e32 v64, 16, v37
	v_mul_f32_e32 v61, v69, v61
	v_fmac_f32_e32 v31, v61, v61
	v_cndmask_b32_e64 v53, v53, v61, s[8:9]
	v_mul_f32_e32 v61, 0x3d372713, v34
	v_mul_f32_e32 v61, v61, v34
	v_fma_f32 v61, v61, v34, v34
	v_mul_f32_e32 v61, 0x3fcc422a, v61
	v_mul_f32_e32 v61, 0xbfb8aa3b, v61
	v_exp_f32_e32 v61, v61
	v_and_b32_e32 v37, 0xffff0000, v37
	v_and_b32_e32 v20, 0xffff0000, v20
	v_lshlrev_b32_e32 v66, 16, v21
	v_add_f32_e32 v61, 1.0, v61
	v_rcp_f32_e32 v61, v61
	v_and_b32_e32 v21, 0xffff0000, v21
	v_lshlrev_b32_e32 v67, 16, v22
	v_and_b32_e32 v22, 0xffff0000, v22
	v_mul_f32_e32 v34, v61, v34
	v_fmac_f32_e32 v31, v34, v34
	v_cndmask_b32_e64 v26, v26, v34, s[8:9]
	v_mul_f32_e32 v34, 0x3d372713, v62
	v_mul_f32_e32 v34, v34, v62
	v_fma_f32 v34, v34, v62, v62
	v_mul_f32_e32 v34, 0x3fcc422a, v34
	v_mul_f32_e32 v34, 0xbfb8aa3b, v34
	v_exp_f32_e32 v34, v34
	v_lshlrev_b32_e32 v68, 16, v23
	v_and_b32_e32 v23, 0xffff0000, v23
	v_add_f32_e32 v34, 1.0, v34
	v_rcp_f32_e32 v34, v34
; __device__ __forceinline__ float bflo(unsigned w) { return __uint_as_float(w << 16); }
; __device__ __forceinline__ float bfhi(unsigned w) { return __uint_as_float(w & 0xffff0000u); }
; __device__ __forceinline__ float gelu_t(float x) { return x * sigm(1.5957691216057308f * (x + 0.044715f * x * x * x)); }
; __device__ __forceinline__ void gmlp_item(const Params& p, int l, int item, LAS unsigned char* lds) {
;     ...
;       for (int gg = 0; gg < 4; ++gg) { const u32x4 w0 = *(const u32x4*)(vp + gg * 64), w1 = *(const u32x4*)(vp + gg * 64 + 8);
;           const float v[16] = {bflo(w0.x), bfhi(w0.x), bflo(w0.y), bfhi(w0.y), bflo(w0.z), bfhi(w0.z), bflo(w0.w), bfhi(w0.w),
;                                bflo(w1.x), bfhi(w1.x), bflo(w1.y), bfhi(w1.y), bflo(w1.z), bfhi(w1.z), bflo(w1.w), bfhi(w1.w)};
; #pragma unroll
;           for (int i = 0; i < 16; ++i) { const float ge = gelu_t(v[i]); ss += ge * ge; keep[i] = (gg == g) ? ge : keep[i]; } }
	s_nop 0
	v_mul_f32_e32 v34, v34, v62
	v_fmac_f32_e32 v31, v34, v34
	v_cndmask_b32_e64 v27, v27, v34, s[8:9]
	v_mul_f32_e32 v34, 0x3d372713, v35
	v_mul_f32_e32 v34, v34, v35
	v_fma_f32 v34, v34, v35, v35
	v_mul_f32_e32 v34, 0x3fcc422a, v34
	v_mul_f32_e32 v34, 0xbfb8aa3b, v34
	v_exp_f32_e32 v34, v34
	s_nop 0
	v_add_f32_e32 v34, 1.0, v34
	v_rcp_f32_e32 v34, v34
	s_nop 0
	v_mul_f32_e32 v34, v34, v35
	v_fmac_f32_e32 v31, v34, v34
	v_cndmask_b32_e64 v54, v54, v34, s[8:9]
	v_mul_f32_e32 v34, 0x3d372713, v63
	v_mul_f32_e32 v34, v34, v63
	v_fma_f32 v34, v34, v63, v63
	v_mul_f32_e32 v34, 0x3fcc422a, v34
	v_mul_f32_e32 v34, 0xbfb8aa3b, v34
	v_exp_f32_e32 v34, v34
	s_nop 0
	v_add_f32_e32 v34, 1.0, v34
	v_rcp_f32_e32 v34, v34
	s_nop 0
	v_mul_f32_e32 v34, v34, v63
	v_fmac_f32_e32 v31, v34, v34
	v_cndmask_b32_e64 v38, v38, v34, s[8:9]
	v_mul_f32_e32 v34, 0x3d372713, v36
	v_mul_f32_e32 v34, v34, v36
	v_fma_f32 v34, v34, v36, v36
	v_mul_f32_e32 v34, 0x3fcc422a, v34
	v_mul_f32_e32 v34, 0xbfb8aa3b, v34
	v_exp_f32_e32 v34, v34
	s_nop 0
	v_add_f32_e32 v34, 1.0, v34
	v_rcp_f32_e32 v34, v34
	s_nop 0
	v_mul_f32_e32 v34, v34, v36
	v_fmac_f32_e32 v31, v34, v34
	v_cndmask_b32_e64 v61, v55, v34, s[8:9]
	v_mul_f32_e32 v34, 0x3d372713, v64
	v_mul_f32_e32 v34, v34, v64
	v_fma_f32 v34, v34, v64, v64
	v_mul_f32_e32 v34, 0x3fcc422a, v34
	v_mul_f32_e32 v34, 0xbfb8aa3b, v34
	v_exp_f32_e32 v34, v34
	s_nop 0
	v_add_f32_e32 v34, 1.0, v34
	v_rcp_f32_e32 v34, v34
	s_nop 0
	v_mul_f32_e32 v34, v34, v64
	v_fmac_f32_e32 v31, v34, v34
	v_cndmask_b32_e64 v39, v39, v34, s[8:9]
	v_mul_f32_e32 v34, 0x3d372713, v37
	v_mul_f32_e32 v34, v34, v37
	v_fma_f32 v34, v34, v37, v37
	v_mul_f32_e32 v34, 0x3fcc422a, v34
	v_mul_f32_e32 v34, 0xbfb8aa3b, v34
	v_exp_f32_e32 v34, v34
	s_nop 0
	v_add_f32_e32 v34, 1.0, v34
	v_rcp_f32_e32 v34, v34
	s_nop 0
	v_mul_f32_e32 v34, v34, v37
	v_fmac_f32_e32 v31, v34, v34
	v_cndmask_b32_e64 v62, v56, v34, s[8:9]
	v_mul_f32_e32 v34, 0x3d372713, v65
	v_mul_f32_e32 v34, v34, v65
	v_fma_f32 v34, v34, v65, v65
	v_mul_f32_e32 v34, 0x3fcc422a, v34
	v_mul_f32_e32 v34, 0xbfb8aa3b, v34
	v_exp_f32_e32 v34, v34
	s_nop 0
	v_add_f32_e32 v34, 1.0, v34
	v_rcp_f32_e32 v34, v34
	s_nop 0
	v_mul_f32_e32 v34, v34, v65
	v_fmac_f32_e32 v31, v34, v34
	v_cndmask_b32_e64 v49, v49, v34, s[8:9]
	v_mul_f32_e32 v34, 0x3d372713, v20
	v_mul_f32_e32 v34, v34, v20
	v_fma_f32 v34, v34, v20, v20
	v_mul_f32_e32 v34, 0x3fcc422a, v34
	v_mul_f32_e32 v34, 0xbfb8aa3b, v34
	v_exp_f32_e32 v34, v34
	s_nop 0
	v_add_f32_e32 v34, 1.0, v34
	v_rcp_f32_e32 v34, v34
	s_nop 0
	v_mul_f32_e32 v20, v34, v20
	v_fmac_f32_e32 v31, v20, v20
	v_cndmask_b32_e64 v63, v57, v20, s[8:9]
	v_mul_f32_e32 v20, 0x3d372713, v66
	v_mul_f32_e32 v20, v20, v66
	v_fma_f32 v20, v20, v66, v66
	v_mul_f32_e32 v20, 0x3fcc422a, v20
	v_mul_f32_e32 v20, 0xbfb8aa3b, v20
	v_exp_f32_e32 v20, v20
	s_nop 0
	v_add_f32_e32 v20, 1.0, v20
	v_rcp_f32_e32 v20, v20
	s_nop 0
	v_mul_f32_e32 v20, v20, v66
	v_fmac_f32_e32 v31, v20, v20
	v_cndmask_b32_e64 v64, v50, v20, s[8:9]
	v_mul_f32_e32 v20, 0x3d372713, v21
	v_mul_f32_e32 v20, v20, v21
	v_fma_f32 v20, v20, v21, v21
	v_mul_f32_e32 v20, 0x3fcc422a, v20
	v_mul_f32_e32 v20, 0xbfb8aa3b, v20
	v_exp_f32_e32 v20, v20
	s_nop 0
	v_add_f32_e32 v20, 1.0, v20
	v_rcp_f32_e32 v20, v20
	s_nop 0
	v_mul_f32_e32 v20, v20, v21
	v_fmac_f32_e32 v31, v20, v20
	v_cndmask_b32_e64 v65, v58, v20, s[8:9]
	v_mul_f32_e32 v20, 0x3d372713, v67
	v_mul_f32_e32 v20, v20, v67
	v_fma_f32 v20, v20, v67, v67
	v_mul_f32_e32 v20, 0x3fcc422a, v20
	v_mul_f32_e32 v20, 0xbfb8aa3b, v20
	v_exp_f32_e32 v20, v20
	s_nop 0
	v_add_f32_e32 v20, 1.0, v20
	v_rcp_f32_e32 v20, v20
	s_nop 0
	v_mul_f32_e32 v20, v20, v67
	v_fmac_f32_e32 v31, v20, v20
	v_cndmask_b32_e64 v66, v51, v20, s[8:9]
	v_mul_f32_e32 v20, 0x3d372713, v22
	v_mul_f32_e32 v20, v20, v22
	v_fma_f32 v20, v20, v22, v22
	v_mul_f32_e32 v20, 0x3fcc422a, v20
	v_mul_f32_e32 v20, 0xbfb8aa3b, v20
	v_exp_f32_e32 v20, v20
	s_nop 0
	v_add_f32_e32 v20, 1.0, v20
	v_rcp_f32_e32 v20, v20
	s_nop 0
	v_mul_f32_e32 v20, v20, v22
	v_fmac_f32_e32 v31, v20, v20
	v_cndmask_b32_e64 v59, v59, v20, s[8:9]
	v_mul_f32_e32 v20, 0x3d372713, v68
	v_mul_f32_e32 v20, v20, v68
	v_fma_f32 v20, v20, v68, v68
	v_mul_f32_e32 v20, 0x3fcc422a, v20
	v_mul_f32_e32 v20, 0xbfb8aa3b, v20
	v_exp_f32_e32 v20, v20
	s_nop 0
	v_add_f32_e32 v20, 1.0, v20
	v_rcp_f32_e32 v20, v20
	s_nop 0
	v_mul_f32_e32 v20, v20, v68
	v_fmac_f32_e32 v31, v20, v20
	v_cndmask_b32_e64 v67, v52, v20, s[8:9]
	v_mul_f32_e32 v20, 0x3d372713, v23
	v_mul_f32_e32 v20, v20, v23
	v_fma_f32 v20, v20, v23, v23
	v_mul_f32_e32 v20, 0x3fcc422a, v20
	v_mul_f32_e32 v20, 0xbfb8aa3b, v20
	v_exp_f32_e32 v20, v20
	s_nop 0
	v_add_f32_e32 v20, 1.0, v20
	v_rcp_f32_e32 v20, v20
	s_nop 0
	v_mul_f32_e32 v20, v20, v23
	v_fmac_f32_e32 v31, v20, v20
	v_cndmask_b32_e64 v60, v60, v20, s[8:9]
	s_waitcnt vmcnt(2)
; __device__ __forceinline__ float bflo(unsigned w) { return __uint_as_float(w << 16); }
; __device__ __forceinline__ float bfhi(unsigned w) { return __uint_as_float(w & 0xffff0000u); }
; __device__ __forceinline__ float gelu_t(float x) { return x * sigm(1.5957691216057308f * (x + 0.044715f * x * x * x)); }
; __device__ __forceinline__ void gmlp_item(const Params& p, int l, int item, LAS unsigned char* lds) {
;     ...
;       for (int gg = 0; gg < 4; ++gg) { const u32x4 w0 = *(const u32x4*)(vp + gg * 64), w1 = *(const u32x4*)(vp + gg * 64 + 8);
;           const float v[16] = {bflo(w0.x), bfhi(w0.x), bflo(w0.y), bfhi(w0.y), bflo(w0.z), bfhi(w0.z), bflo(w0.w), bfhi(w0.w),
;                                bflo(w1.x), bfhi(w1.x), bflo(w1.y), bfhi(w1.y), bflo(w1.z), bfhi(w1.z), bflo(w1.w), bfhi(w1.w)};
; #pragma unroll
;           for (int i = 0; i < 16; ++i) { const float ge = gelu_t(v[i]); ss += ge * ge; keep[i] = (gg == g) ? ge : keep[i]; } }
	v_mov_b32_e32 v20, v110
	v_mov_b32_e32 v21, v111
	v_mov_b32_e32 v22, v112
	v_mov_b32_e32 v23, v113
	v_mov_b32_e32 v34, v114
	v_mov_b32_e32 v35, v115
	v_mov_b32_e32 v36, v116
	v_mov_b32_e32 v37, v117
	s_cselect_b64 s[8:9], -1, 0
	s_cmp_eq_u32 s37, 3
	v_lshlrev_b32_e32 v69, 16, v20
	v_lshlrev_b32_e32 v50, 16, v34
	v_mul_f32_e32 v55, 0x3d372713, v50
	v_mul_f32_e32 v55, v55, v50
	v_fma_f32 v55, v55, v50, v50
	v_mul_f32_e32 v55, 0x3fcc422a, v55
	v_mul_f32_e32 v55, 0xbfb8aa3b, v55
	v_exp_f32_e32 v55, v55
	v_and_b32_e32 v34, 0xffff0000, v34
	v_lshlrev_b32_e32 v51, 16, v35
	v_and_b32_e32 v35, 0xffff0000, v35
	v_add_f32_e32 v55, 1.0, v55
	v_rcp_f32_e32 v55, v55
	v_lshlrev_b32_e32 v52, 16, v36
	v_and_b32_e32 v36, 0xffff0000, v36
	v_lshlrev_b32_e32 v68, 16, v37
	v_mul_f32_e32 v50, v55, v50
	v_fmac_f32_e32 v31, v50, v50
	v_cndmask_b32_e64 v58, v53, v50, s[8:9]
	v_mul_f32_e32 v50, 0x3d372713, v34
	v_mul_f32_e32 v50, v50, v34
	v_fma_f32 v50, v50, v34, v34
	v_mul_f32_e32 v50, 0x3fcc422a, v50
	v_mul_f32_e32 v50, 0xbfb8aa3b, v50
	v_exp_f32_e32 v50, v50
	v_and_b32_e32 v37, 0xffff0000, v37
	v_and_b32_e32 v20, 0xffff0000, v20
	v_lshlrev_b32_e32 v70, 16, v21
	v_add_f32_e32 v50, 1.0, v50
	v_rcp_f32_e32 v50, v50
	v_and_b32_e32 v21, 0xffff0000, v21
	v_lshlrev_b32_e32 v71, 16, v22
	v_and_b32_e32 v22, 0xffff0000, v22
	v_mul_f32_e32 v34, v50, v34
	v_cndmask_b32_e64 v57, v26, v34, s[8:9]
	v_mul_f32_e32 v26, 0x3d372713, v51
	v_mul_f32_e32 v26, v26, v51
	v_fma_f32 v26, v26, v51, v51
	v_mul_f32_e32 v26, 0x3fcc422a, v26
	v_mul_f32_e32 v26, 0xbfb8aa3b, v26
	v_exp_f32_e32 v26, v26
	v_fmac_f32_e32 v31, v34, v34
	v_lshlrev_b32_e32 v72, 16, v23
	v_and_b32_e32 v23, 0xffff0000, v23
	v_add_f32_e32 v26, 1.0, v26
	v_rcp_f32_e32 v26, v26
	s_nop 0
	v_mul_f32_e32 v26, v26, v51
	v_fmac_f32_e32 v31, v26, v26
	v_cndmask_b32_e64 v56, v27, v26, s[8:9]
	v_mul_f32_e32 v26, 0x3d372713, v35
	v_mul_f32_e32 v26, v26, v35
	v_fma_f32 v26, v26, v35, v35
	v_mul_f32_e32 v26, 0x3fcc422a, v26
	v_mul_f32_e32 v26, 0xbfb8aa3b, v26
	v_exp_f32_e32 v26, v26
	s_nop 0
	v_add_f32_e32 v26, 1.0, v26
	v_rcp_f32_e32 v26, v26
	s_nop 0
	v_mul_f32_e32 v26, v26, v35
	v_fmac_f32_e32 v31, v26, v26
	v_cndmask_b32_e64 v55, v54, v26, s[8:9]
	v_mul_f32_e32 v26, 0x3d372713, v52
	v_mul_f32_e32 v26, v26, v52
	v_fma_f32 v26, v26, v52, v52
	v_mul_f32_e32 v26, 0x3fcc422a, v26
	v_mul_f32_e32 v26, 0xbfb8aa3b, v26
	v_exp_f32_e32 v26, v26
	s_nop 0
	v_add_f32_e32 v26, 1.0, v26
	v_rcp_f32_e32 v26, v26
	s_nop 0
	v_mul_f32_e32 v26, v26, v52
	v_fmac_f32_e32 v31, v26, v26
	v_cndmask_b32_e64 v54, v38, v26, s[8:9]
	v_mul_f32_e32 v26, 0x3d372713, v36
	v_mul_f32_e32 v26, v26, v36
	v_fma_f32 v26, v26, v36, v36
	v_mul_f32_e32 v26, 0x3fcc422a, v26
	v_mul_f32_e32 v26, 0xbfb8aa3b, v26
	v_exp_f32_e32 v26, v26
	s_nop 0
	v_add_f32_e32 v26, 1.0, v26
	v_rcp_f32_e32 v26, v26
	s_nop 0
	v_mul_f32_e32 v26, v26, v36
	v_fmac_f32_e32 v31, v26, v26
	v_cndmask_b32_e64 v53, v61, v26, s[8:9]
	v_mul_f32_e32 v26, 0x3d372713, v68
	v_mul_f32_e32 v26, v26, v68
	v_fma_f32 v26, v26, v68, v68
	v_mul_f32_e32 v26, 0x3fcc422a, v26
	v_mul_f32_e32 v26, 0xbfb8aa3b, v26
	v_exp_f32_e32 v26, v26
	s_nop 0
	v_add_f32_e32 v26, 1.0, v26
	v_rcp_f32_e32 v26, v26
	s_nop 0
	v_mul_f32_e32 v26, v26, v68
	v_fmac_f32_e32 v31, v26, v26
	v_cndmask_b32_e64 v52, v39, v26, s[8:9]
	v_mul_f32_e32 v26, 0x3d372713, v37
	v_mul_f32_e32 v26, v26, v37
	v_fma_f32 v26, v26, v37, v37
	v_mul_f32_e32 v26, 0x3fcc422a, v26
	v_mul_f32_e32 v26, 0xbfb8aa3b, v26
	v_exp_f32_e32 v26, v26
	s_nop 0
	v_add_f32_e32 v26, 1.0, v26
	v_rcp_f32_e32 v26, v26
	s_nop 0
	v_mul_f32_e32 v26, v26, v37
	v_fmac_f32_e32 v31, v26, v26
	v_cndmask_b32_e64 v51, v62, v26, s[8:9]
	v_mul_f32_e32 v26, 0x3d372713, v69
	v_mul_f32_e32 v26, v26, v69
	v_fma_f32 v26, v26, v69, v69
	v_mul_f32_e32 v26, 0x3fcc422a, v26
	v_mul_f32_e32 v26, 0xbfb8aa3b, v26
	v_exp_f32_e32 v26, v26
	s_nop 0
	v_add_f32_e32 v26, 1.0, v26
	v_rcp_f32_e32 v26, v26
	s_nop 0
	v_mul_f32_e32 v26, v26, v69
	v_fmac_f32_e32 v31, v26, v26
	v_cndmask_b32_e64 v49, v49, v26, s[8:9]
	v_mul_f32_e32 v26, 0x3d372713, v20
	v_mul_f32_e32 v26, v26, v20
	v_fma_f32 v26, v26, v20, v20
	v_mul_f32_e32 v26, 0x3fcc422a, v26
	v_mul_f32_e32 v26, 0xbfb8aa3b, v26
	v_exp_f32_e32 v26, v26
	s_nop 0
	v_add_f32_e32 v26, 1.0, v26
	v_rcp_f32_e32 v26, v26
	s_nop 0
	v_mul_f32_e32 v20, v26, v20
	v_fmac_f32_e32 v31, v20, v20
	v_cndmask_b32_e64 v50, v63, v20, s[8:9]
	v_mul_f32_e32 v20, 0x3d372713, v70
	v_mul_f32_e32 v20, v20, v70
	v_fma_f32 v20, v20, v70, v70
	v_mul_f32_e32 v20, 0x3fcc422a, v20
	v_mul_f32_e32 v20, 0xbfb8aa3b, v20
	v_exp_f32_e32 v20, v20
	s_nop 0
	v_add_f32_e32 v20, 1.0, v20
	v_rcp_f32_e32 v20, v20
	s_nop 0
	v_mul_f32_e32 v20, v20, v70
	v_fmac_f32_e32 v31, v20, v20
	v_cndmask_b32_e64 v38, v64, v20, s[8:9]
	v_mul_f32_e32 v20, 0x3d372713, v21
	v_mul_f32_e32 v20, v20, v21
	v_fma_f32 v20, v20, v21, v21
	v_mul_f32_e32 v20, 0x3fcc422a, v20
	v_mul_f32_e32 v20, 0xbfb8aa3b, v20
	v_exp_f32_e32 v20, v20
	s_nop 0
	v_add_f32_e32 v20, 1.0, v20
	v_rcp_f32_e32 v20, v20
	s_nop 0
	v_mul_f32_e32 v20, v20, v21
	v_fmac_f32_e32 v31, v20, v20
	v_cndmask_b32_e64 v39, v65, v20, s[8:9]
	v_mul_f32_e32 v20, 0x3d372713, v71
	v_mul_f32_e32 v20, v20, v71
	v_fma_f32 v20, v20, v71, v71
	v_mul_f32_e32 v20, 0x3fcc422a, v20
	v_mul_f32_e32 v20, 0xbfb8aa3b, v20
	v_exp_f32_e32 v20, v20
	s_nop 0
	v_add_f32_e32 v20, 1.0, v20
	v_rcp_f32_e32 v20, v20
	s_nop 0
	v_mul_f32_e32 v20, v20, v71
	v_fmac_f32_e32 v31, v20, v20
	v_cndmask_b32_e64 v35, v66, v20, s[8:9]
	v_mul_f32_e32 v20, 0x3d372713, v22
	v_mul_f32_e32 v20, v20, v22
	v_fma_f32 v20, v20, v22, v22
	v_mul_f32_e32 v20, 0x3fcc422a, v20
	v_mul_f32_e32 v20, 0xbfb8aa3b, v20
	v_exp_f32_e32 v20, v20
	s_nop 0
	v_add_f32_e32 v20, 1.0, v20
	v_rcp_f32_e32 v20, v20
	s_nop 0
	v_mul_f32_e32 v20, v20, v22
	v_fmac_f32_e32 v31, v20, v20
	v_cndmask_b32_e64 v37, v59, v20, s[8:9]
	v_mul_f32_e32 v20, 0x3d372713, v72
	v_mul_f32_e32 v20, v20, v72
	v_fma_f32 v20, v20, v72, v72
	v_mul_f32_e32 v20, 0x3fcc422a, v20
	v_mul_f32_e32 v20, 0xbfb8aa3b, v20
	v_exp_f32_e32 v20, v20
	s_nop 0
	v_add_f32_e32 v20, 1.0, v20
	v_rcp_f32_e32 v20, v20
	s_nop 0
	v_mul_f32_e32 v20, v20, v72
	v_fmac_f32_e32 v31, v20, v20
	v_cndmask_b32_e64 v34, v67, v20, s[8:9]
	v_mul_f32_e32 v20, 0x3d372713, v23
	v_mul_f32_e32 v20, v20, v23
	v_fma_f32 v20, v20, v23, v23
	v_mul_f32_e32 v20, 0x3fcc422a, v20
	v_mul_f32_e32 v20, 0xbfb8aa3b, v20
	v_exp_f32_e32 v20, v20
	s_nop 0
	v_add_f32_e32 v20, 1.0, v20
	v_rcp_f32_e32 v20, v20
	s_nop 0
	v_mul_f32_e32 v20, v20, v23
	v_fmac_f32_e32 v31, v20, v20
	v_cndmask_b32_e64 v36, v60, v20, s[8:9]
	s_waitcnt vmcnt(0)
; __device__ __forceinline__ float bflo(unsigned w) { return __uint_as_float(w << 16); }
; __device__ __forceinline__ float bfhi(unsigned w) { return __uint_as_float(w & 0xffff0000u); }
; __device__ __forceinline__ float gelu_t(float x) { return x * sigm(1.5957691216057308f * (x + 0.044715f * x * x * x)); }
; __device__ __forceinline__ void gmlp_item(const Params& p, int l, int item, LAS unsigned char* lds) {
;     ...
;       for (int gg = 0; gg < 4; ++gg) { const u32x4 w0 = *(const u32x4*)(vp + gg * 64), w1 = *(const u32x4*)(vp + gg * 64 + 8);
;           const float v[16] = {bflo(w0.x), bfhi(w0.x), bflo(w0.y), bfhi(w0.y), bflo(w0.z), bfhi(w0.z), bflo(w0.w), bfhi(w0.w),
;                                bflo(w1.x), bfhi(w1.x), bflo(w1.y), bfhi(w1.y), bflo(w1.z), bfhi(w1.z), bflo(w1.w), bfhi(w1.w)};
; #pragma unroll
;           for (int i = 0; i < 16; ++i) { const float ge = gelu_t(v[i]); ss += ge * ge; keep[i] = (gg == g) ? ge : keep[i]; } }
	v_mov_b32_e32 v20, v118
	v_mov_b32_e32 v21, v119
	v_mov_b32_e32 v22, v120
	v_mov_b32_e32 v23, v121
	s_nop 0
	v_mov_b32_e32 v24, v122
	v_mov_b32_e32 v25, v123
	v_mov_b32_e32 v26, v124
	v_mov_b32_e32 v27, v125
	s_cselect_b64 s[8:9], -1, 0
	s_waitcnt vmcnt(0)
	v_lshlrev_b32_e32 v59, 16, v24
	v_mul_f32_e32 v63, 0x3d372713, v59
	v_mul_f32_e32 v63, v63, v59
	v_fma_f32 v63, v63, v59, v59
	v_mul_f32_e32 v63, 0x3fcc422a, v63
	v_mul_f32_e32 v63, 0xbfb8aa3b, v63
	v_exp_f32_e32 v63, v63
	v_and_b32_e32 v24, 0xffff0000, v24
	v_lshlrev_b32_e32 v60, 16, v25
	v_and_b32_e32 v25, 0xffff0000, v25
	v_add_f32_e32 v63, 1.0, v63
	v_rcp_f32_e32 v63, v63
	v_lshlrev_b32_e32 v61, 16, v26
	v_and_b32_e32 v26, 0xffff0000, v26
	v_lshlrev_b32_e32 v62, 16, v27
	v_mul_f32_e32 v59, v63, v59
	v_fmac_f32_e32 v31, v59, v59
	v_cndmask_b32_e64 v58, v58, v59, s[8:9]
	v_mul_f32_e32 v59, 0x3d372713, v24
	v_mul_f32_e32 v59, v59, v24
	v_fma_f32 v59, v59, v24, v24
	v_mul_f32_e32 v59, 0x3fcc422a, v59
	v_mul_f32_e32 v59, 0xbfb8aa3b, v59
	v_exp_f32_e32 v59, v59
	v_and_b32_e32 v27, 0xffff0000, v27
	v_add_f32_e32 v59, 1.0, v59
	v_rcp_f32_e32 v59, v59
	s_nop 0
	v_mul_f32_e32 v24, v59, v24
	v_fmac_f32_e32 v31, v24, v24
	v_cndmask_b32_e64 v57, v57, v24, s[8:9]
	v_mul_f32_e32 v24, 0x3d372713, v60
	v_mul_f32_e32 v24, v24, v60
	v_fma_f32 v24, v24, v60, v60
	v_mul_f32_e32 v24, 0x3fcc422a, v24
	v_mul_f32_e32 v24, 0xbfb8aa3b, v24
	v_exp_f32_e32 v24, v24
	s_nop 0
	v_add_f32_e32 v24, 1.0, v24
	v_rcp_f32_e32 v24, v24
	s_nop 0
	v_mul_f32_e32 v24, v24, v60
	v_fmac_f32_e32 v31, v24, v24
	v_cndmask_b32_e64 v56, v56, v24, s[8:9]
	v_mul_f32_e32 v24, 0x3d372713, v25
	v_mul_f32_e32 v24, v24, v25
	v_fma_f32 v24, v24, v25, v25
	v_mul_f32_e32 v24, 0x3fcc422a, v24
	v_mul_f32_e32 v24, 0xbfb8aa3b, v24
	v_exp_f32_e32 v24, v24
	s_nop 0
	v_add_f32_e32 v24, 1.0, v24
	v_rcp_f32_e32 v24, v24
	s_nop 0
	v_mul_f32_e32 v24, v24, v25
	v_fmac_f32_e32 v31, v24, v24
	v_cndmask_b32_e64 v55, v55, v24, s[8:9]
	v_mul_f32_e32 v24, 0x3d372713, v61
	v_mul_f32_e32 v24, v24, v61
	v_fma_f32 v24, v24, v61, v61
	v_mul_f32_e32 v24, 0x3fcc422a, v24
	v_mul_f32_e32 v24, 0xbfb8aa3b, v24
	v_exp_f32_e32 v24, v24
	v_lshlrev_b32_e32 v25, 16, v20
	v_add_f32_e32 v24, 1.0, v24
	v_rcp_f32_e32 v24, v24
	s_nop 0
	v_mul_f32_e32 v24, v24, v61
	v_fmac_f32_e32 v31, v24, v24
	v_cndmask_b32_e64 v54, v54, v24, s[8:9]
	v_mul_f32_e32 v24, 0x3d372713, v26
	v_mul_f32_e32 v24, v24, v26
	v_fma_f32 v24, v24, v26, v26
	v_mul_f32_e32 v24, 0x3fcc422a, v24
	v_mul_f32_e32 v24, 0xbfb8aa3b, v24
	v_exp_f32_e32 v24, v24
	s_nop 0
	v_add_f32_e32 v24, 1.0, v24
	v_rcp_f32_e32 v24, v24
	s_nop 0
	v_mul_f32_e32 v24, v24, v26
	v_fmac_f32_e32 v31, v24, v24
	v_cndmask_b32_e64 v53, v53, v24, s[8:9]
	v_mul_f32_e32 v24, 0x3d372713, v62
	v_mul_f32_e32 v24, v24, v62
	v_fma_f32 v24, v24, v62, v62
	v_mul_f32_e32 v24, 0x3fcc422a, v24
	v_mul_f32_e32 v24, 0xbfb8aa3b, v24
	v_exp_f32_e32 v24, v24
	v_mov_b32_e32 v26, v25
	v_add_f32_e32 v24, 1.0, v24
	v_rcp_f32_e32 v24, v24
	s_nop 0
	v_mul_f32_e32 v24, v24, v62
	v_fmac_f32_e32 v31, v24, v24
	v_cndmask_b32_e64 v52, v52, v24, s[8:9]
	v_mul_f32_e32 v24, 0x3d372713, v27
	v_mul_f32_e32 v24, v24, v27
	v_fma_f32 v24, v24, v27, v27
	v_mul_f32_e32 v24, 0x3fcc422a, v24
	v_mul_f32_e32 v24, 0xbfb8aa3b, v24
	v_exp_f32_e32 v24, v24
	s_nop 0
	v_add_f32_e32 v24, 1.0, v24
	v_rcp_f32_e32 v24, v24
	s_nop 0
	v_mul_f32_e32 v24, v24, v27
	v_fmac_f32_e32 v31, v24, v24
	v_cndmask_b32_e64 v51, v51, v24, s[8:9]
	v_and_b32_e32 v24, 0xffff0000, v20
	v_mul_f32_e32 v20, 0x3d372713, v25
	v_mul_f32_e32 v20, v20, v25
	v_fmac_f32_e32 v26, v20, v26
	v_mul_f32_e32 v20, 0x3fcc422a, v26
	v_mul_f32_e32 v20, 0xbfb8aa3b, v20
	v_exp_f32_e32 v20, v20
	v_mov_b32_e32 v26, v24
	v_add_f32_e32 v20, 1.0, v20
	v_rcp_f32_e32 v27, v20
	v_mul_f32_e32 v20, 0x3d372713, v24
	v_mul_f32_e32 v20, v20, v24
	v_fmac_f32_e32 v26, v20, v26
	v_mul_f32_e32 v20, 0x3fcc422a, v26
	v_mul_f32_e32 v20, 0xbfb8aa3b, v20
	v_exp_f32_e32 v20, v20
	s_nop 0
	v_add_f32_e32 v20, 1.0, v20
	v_rcp_f32_e32 v26, v20
	s_nop 0
	v_pk_mul_f32 v[24:25], v[26:27], v[24:25]
	s_nop 0
	v_pk_mul_f32 v[26:27], v[24:25], v[24:25]
	v_cndmask_b32_e64 v49, v49, v25, s[8:9]
	v_add_f32_e32 v20, v27, v31
	v_lshlrev_b32_e32 v25, 16, v21
	v_add_f32_e32 v31, v26, v20
	v_cndmask_b32_e64 v20, v50, v24, s[8:9]
	v_and_b32_e32 v24, 0xffff0000, v21
	v_mul_f32_e32 v21, 0x3d372713, v25
	v_mul_f32_e32 v21, v21, v25
	v_mov_b32_e32 v26, v25
	v_fmac_f32_e32 v26, v21, v26
	v_mul_f32_e32 v21, 0x3fcc422a, v26
	v_mul_f32_e32 v21, 0xbfb8aa3b, v21
	v_exp_f32_e32 v21, v21
	v_mov_b32_e32 v26, v24
	v_add_f32_e32 v21, 1.0, v21
	v_rcp_f32_e32 v27, v21
	v_mul_f32_e32 v21, 0x3d372713, v24
	v_mul_f32_e32 v21, v21, v24
	v_fmac_f32_e32 v26, v21, v26
	v_mul_f32_e32 v21, 0x3fcc422a, v26
	v_mul_f32_e32 v21, 0xbfb8aa3b, v21
	v_exp_f32_e32 v21, v21
	s_nop 0
	v_add_f32_e32 v21, 1.0, v21
	v_rcp_f32_e32 v26, v21
	s_nop 0
	v_pk_mul_f32 v[24:25], v[26:27], v[24:25]
	s_nop 0
	v_pk_mul_f32 v[26:27], v[24:25], v[24:25]
	s_nop 0
	v_add_f32_e32 v21, v27, v31
	v_cndmask_b32_e64 v31, v38, v25, s[8:9]
	v_lshlrev_b32_e32 v25, 16, v22
	v_add_f32_e32 v38, v26, v21
	v_cndmask_b32_e64 v21, v39, v24, s[8:9]
	v_and_b32_e32 v24, 0xffff0000, v22
	v_mul_f32_e32 v22, 0x3d372713, v25
	v_mul_f32_e32 v22, v22, v25
	v_mov_b32_e32 v26, v25
	v_fmac_f32_e32 v26, v22, v26
	v_mul_f32_e32 v22, 0x3fcc422a, v26
	v_mul_f32_e32 v22, 0xbfb8aa3b, v22
	v_exp_f32_e32 v22, v22
	v_mov_b32_e32 v26, v24
	v_add_f32_e32 v22, 1.0, v22
	v_rcp_f32_e32 v27, v22
	v_mul_f32_e32 v22, 0x3d372713, v24
	v_mul_f32_e32 v22, v22, v24
	v_fmac_f32_e32 v26, v22, v26
	v_mul_f32_e32 v22, 0x3fcc422a, v26
	v_mul_f32_e32 v22, 0xbfb8aa3b, v22
; __device__ __forceinline__ bf16_t f2bf(float f) { return (bf16_t)(pk2(f, 0.f) & 0xffffu); }
; __device__ __forceinline__ void lds_barrier() { asm volatile("s_waitcnt lgkmcnt(0)" ::: "memory"); __builtin_amdgcn_s_barrier(); asm volatile("" ::: "memory"); }
; __device__ __forceinline__ void gmlp_item(const Params& p, int l, int item, LAS unsigned char* lds) {
;     ...
;       ss += __shfl_xor(ss, 1); ss += __shfl_xor(ss, 2);
;       const float rstd = rsqrtf(ss * (1.f / 256.f) + EPS);
;       const float* ng = p.gm_norm_g + l * 256 + g * 64 + qd * 16;
; #pragma unroll
;       for (int i = 0; i < 16; ++i) vnT[(qd * 16 + i) * 136 + pp] = f2bf(keep[i] * rstd * ng[i]);
;     }
;     lds_barrier();
;     { f32x4 acc[4];
; #pragma unroll
;       for (int ct = 0; ct < 4; ++ct) acc[ct] = ZERO4;
	v_exp_f32_e32 v22, v22
	s_nop 0
	v_add_f32_e32 v22, 1.0, v22
	v_rcp_f32_e32 v26, v22
	s_nop 0
	v_pk_mul_f32 v[24:25], v[26:27], v[24:25]
	s_nop 0
	v_pk_mul_f32 v[26:27], v[24:25], v[24:25]
	v_cndmask_b32_e64 v22, v35, v25, s[8:9]
	v_add_f32_e32 v27, v27, v38
	v_add_f32_e32 v25, v26, v27
	v_lshlrev_b32_e32 v27, 16, v23
	v_and_b32_e32 v26, 0xffff0000, v23
	v_mul_f32_e32 v23, 0x3d372713, v27
	v_mul_f32_e32 v23, v23, v27
	v_mov_b32_e32 v35, v27
	v_fmac_f32_e32 v35, v23, v35
	v_mul_f32_e32 v23, 0x3fcc422a, v35
	v_mul_f32_e32 v23, 0xbfb8aa3b, v23
	v_exp_f32_e32 v23, v23
	v_mov_b32_e32 v35, v26
	v_cndmask_b32_e64 v24, v37, v24, s[8:9]
	v_add_f32_e32 v23, 1.0, v23
	v_rcp_f32_e32 v39, v23
	v_mul_f32_e32 v23, 0x3d372713, v26
	v_mul_f32_e32 v23, v23, v26
	v_fmac_f32_e32 v35, v23, v35
	v_mul_f32_e32 v23, 0x3fcc422a, v35
	v_mul_f32_e32 v23, 0xbfb8aa3b, v23
	v_exp_f32_e32 v23, v23
	s_nop 0
	v_add_f32_e32 v23, 1.0, v23
	v_rcp_f32_e32 v38, v23
	s_nop 0
	v_pk_mul_f32 v[38:39], v[38:39], v[26:27]
	s_nop 0
	v_cndmask_b32_e64 v26, v34, v39, s[8:9]
	v_and_b32_e32 v34, 64, v207
	v_pk_mul_f32 v[60:61], v[38:39], v[38:39]
	v_xor_b32_e32 v27, 1, v207
	v_add_u32_e32 v34, 64, v34
	v_add_f32_e32 v23, v61, v25
	v_cndmask_b32_e64 v25, v36, v38, s[8:9]
	v_cmp_lt_i32_e64 s[8:9], v27, v34
	v_add_f32_e32 v23, v60, v23
	v_mov_b32_e32 v39, 0
	v_cndmask_b32_e64 v27, v207, v27, s[8:9]
	v_lshlrev_b32_e32 v27, 2, v27
	ds_bpermute_b32 v27, v27, v23
	s_waitcnt lgkmcnt(0)
	v_add_f32_e32 v23, v23, v27
	v_xor_b32_e32 v27, 2, v207
	v_cmp_lt_i32_e64 s[8:9], v27, v34
	s_nop 1
	v_cndmask_b32_e64 v27, v207, v27, s[8:9]
	v_lshlrev_b32_e32 v27, 2, v27
	ds_bpermute_b32 v27, v27, v23
	s_waitcnt lgkmcnt(0)
	v_add_f32_e32 v23, v23, v27
	v_fmamk_f32 v23, v23, 0x3b800000, v204
	v_cmp_gt_f32_e64 s[8:9], s93, v23
	v_mul_f32_e32 v27, 0x4b800000, v23
	s_nop 0
	v_cndmask_b32_e64 v23, v23, v27, s[8:9]
	v_rsq_f32_e32 v23, v23
	s_nop 0
	v_mul_f32_e32 v27, 0x45800000, v23
	v_cndmask_b32_e64 v27, v23, v27, s[8:9]
	s_lshl_b64 s[8:9], s[28:29], 2
	s_add_u32 s0, s23, s8
	s_addc_u32 s9, s36, s9
	s_lshl_b32 s8, s37, 8
	s_add_u32 s8, s0, s8
	s_addc_u32 s9, s9, 0
	v_lshlrev_b32_e32 v23, 2, v29
	global_load_dwordx4 v[74:77], v23, s[8:9]
	global_load_dwordx4 v[78:81], v23, s[8:9] offset:16
	global_load_dwordx4 v[82:85], v23, s[8:9] offset:32
	global_load_dwordx4 v[86:89], v23, s[8:9] offset:48
	v_mul_u32_u24_e32 v29, 0x110, v29
	v_add3_u32 v29, 0, v30, v29
	v_mul_f32_e32 v30, v57, v27
	v_mul_f32_e32 v38, v58, v27
	v_mul_f32_e32 v20, v20, v27
	s_movk_i32 s0, 0x110
	s_waitcnt vmcnt(3)
	v_mov_b32_e32 v34, v74
	v_mov_b32_e32 v35, v75
	v_mov_b32_e32 v36, v76
	v_mov_b32_e32 v37, v77
	v_mul_f32_e32 v30, v35, v30
	v_cvt_pk_bf16_f32 v30, v30, v2
	ds_write_b16 v29, v30 offset:272
	v_mul_f32_e32 v30, v56, v27
	v_mul_f32_e32 v30, v36, v30
	v_mul_f32_e32 v34, v34, v38
	v_cvt_pk_bf16_f32 v30, v30, v2
	v_cvt_pk_bf16_f32 v34, v34, v2
	ds_write_b16 v29, v30 offset:544
	v_mul_f32_e32 v30, v55, v27
	ds_write_b16 v29, v34
	v_mul_f32_e32 v30, v37, v30
	v_cvt_pk_bf16_f32 v30, v30, v2
	ds_write_b16 v29, v30 offset:816
	v_mul_f32_e32 v30, v54, v27
	v_mov_b32_e32 v38, 0
	s_waitcnt vmcnt(2)
	v_mov_b32_e32 v34, v78
	v_mov_b32_e32 v35, v79
	v_mov_b32_e32 v36, v80
	v_mov_b32_e32 v37, v81
	v_mul_f32_e32 v30, v34, v30
	v_cvt_pk_bf16_f32 v30, v30, v2
	ds_write_b16 v29, v30 offset:1088
	v_mul_f32_e32 v30, v53, v27
	v_mul_f32_e32 v30, v35, v30
	v_cvt_pk_bf16_f32 v30, v30, v2
	ds_write_b16 v29, v30 offset:1360
	v_mul_f32_e32 v30, v52, v27
	v_mul_f32_e32 v30, v36, v30
	v_cvt_pk_bf16_f32 v30, v30, v2
	ds_write_b16 v29, v30 offset:1632
	v_mul_f32_e32 v30, v51, v27
	v_mul_f32_e32 v30, v37, v30
	v_cvt_pk_bf16_f32 v30, v30, v2
	ds_write_b16 v29, v30 offset:1904
	v_mul_f32_e32 v30, v49, v27
	s_waitcnt vmcnt(1)
	v_mov_b32_e32 v34, v82
	v_mov_b32_e32 v35, v83
	v_mov_b32_e32 v36, v84
	v_mov_b32_e32 v37, v85
	v_mul_f32_e32 v20, v35, v20
	v_cvt_pk_bf16_f32 v20, v20, v2
	ds_write_b16 v29, v20 offset:2448
	v_mul_f32_e32 v20, v31, v27
	v_mul_f32_e32 v20, v36, v20
	v_cvt_pk_bf16_f32 v20, v20, v2
	ds_write_b16 v29, v20 offset:2720
	v_mul_f32_e32 v20, v21, v27
	v_mul_f32_e32 v30, v34, v30
	v_mul_f32_e32 v20, v37, v20
	v_cvt_pk_bf16_f32 v30, v30, v2
	v_cvt_pk_bf16_f32 v20, v20, v2
	ds_write_b16 v29, v30 offset:2176
	ds_write_b16 v29, v20 offset:2992
	v_mul_f32_e32 v30, v22, v27
	v_mov_b32_e32 v36, 0
	v_cmp_lt_i32_e64 s[8:9], -1, v33
	v_mov_b32_e32 v37, 0
	v_mov_b32_e32 v33, v36
	v_mov_b32_e32 v34, v36
	v_mov_b32_e32 v35, v36
	v_mov_b32_e32 v31, v36
	s_waitcnt vmcnt(0)
	v_mov_b32_e32 v20, v86
	v_mov_b32_e32 v21, v87
	v_mov_b32_e32 v22, v88
	v_mov_b32_e32 v23, v89
	v_mul_f32_e32 v20, v20, v30
	v_cvt_pk_bf16_f32 v20, v20, v2
	ds_write_b16 v29, v20 offset:3264
	v_mul_f32_e32 v20, v24, v27
	v_mul_f32_e32 v20, v21, v20
	v_cvt_pk_bf16_f32 v20, v20, v2
	ds_write_b16 v29, v20 offset:3536
	v_mul_f32_e32 v20, v26, v27
	v_mul_f32_e32 v20, v22, v20
	v_cvt_pk_bf16_f32 v20, v20, v2
	ds_write_b16 v29, v20 offset:3808
	v_mul_f32_e32 v20, v25, v27
	v_mul_f32_e32 v20, v23, v20
	v_cvt_pk_bf16_f32 v20, v20, v2
	ds_write_b16 v29, v20 offset:4080
	s_waitcnt lgkmcnt(0)
	s_barrier
	v_add_u32_e32 v20, 0, v28
	v_mad_u32_u24 v49, v32, s0, v20
	v_mov_b32_e32 v32, 0
	v_mov_b32_e32 v28, v36
	v_mov_b32_e32 v29, v36
	v_mov_b32_e32 v30, v36
	v_mov_b32_e32 v24, v36
	v_mov_b32_e32 v25, v36
	v_mov_b32_e32 v26, v36
	v_mov_b32_e32 v27, v36
	v_mov_b32_e32 v20, v36
	v_mov_b32_e32 v21, v36
	v_mov_b32_e32 v22, v36
	v_mov_b32_e32 v23, v36
	s_and_saveexec_b64 s[14:15], s[8:9]
	s_cbranch_execnz .LBB0_344
	s_or_b64 exec, exec, s[14:15]
	s_and_saveexec_b64 s[8:9], s[6:7]
	s_cbranch_execnz .LBB0_345
